# stack10 variant: attention with 4 LDS stages, DMA two tiles ahead, next tile K fragments read before the step barrier (no lgkmcnt wait at the barrier)
# speedup vs baseline: 1.0059x; 1.0059x over previous
.LBB1_520:
	s_and_b64 vcc, exec, s[16:17]
	s_cbranch_vccz .LBB1_490
	s_bfe_u32 s1, s43, 0x30007
	s_ashr_i32 s25, s58, 8
	s_lshl_b32 s5, s58, 7
	s_lshl_b32 s26, s1, 7
	s_lshl_b32 s24, s1, 8
	s_lshl_b32 s1, s25, 12
	s_and_b32 s5, s5, 0xf80
	s_or_b32 s18, s1, s5
	s_mov_b32 s1, s90
	s_mov_b32 s5, s91
	s_mov_b32 s1, -1
	s_mul_i32 s6, s25, 0x880000
	v_mbcnt_lo_u32_b32 v0, s1, 0
	v_readlane_b32 s7, v254, 58
	v_mbcnt_hi_u32_b32 v0, s1, v0
	s_mul_hi_i32 s1, s25, 0x880000
	s_add_u32 s6, s7, s6
	v_readlane_b32 s7, v254, 59
	s_addc_u32 s7, s7, s1
	s_lshl_b32 s1, s58, 2
	s_and_b32 s1, s1, 0x380
	s_lshl_b32 s72, s1, 1
	v_lshl_add_u32 v68, s5, 6, v0
	s_add_u32 s10, s6, s72
	s_addc_u32 s11, s7, 0
	s_lshl_b32 s27, s25, 10
	v_bfe_u32 v0, v68, 3, 3
	s_or_b32 s6, s1, s27
	v_lshl_or_b32 v0, s5, 3, v0
	s_mul_hi_i32 s7, s6, 0x2200
	s_mulk_i32 s6, 0x2200
	v_readlane_b32 s16, v254, 34
	v_lshrrev_b32_e32 v69, 1, v0
	v_readlane_b32 s17, v254, 35
	s_add_u32 s16, s16, s6
	v_xor_b32_e32 v4, v69, v68
	v_ashrrev_i32_e32 v1, 31, v0
	s_addc_u32 s17, s17, s7
	v_lshlrev_b64 v[48:49], 11, v[0:1]
	v_lshlrev_b32_e32 v1, 4, v4
	v_lshl_add_u64 v[2:3], s[10:11], 0, v[48:49]
	v_and_b32_e32 v112, 0x70, v1
	v_mov_b64_e32 v[4:5], s[16:17]
	s_movk_i32 s16, 0x2200
	s_lshl_b32 s7, s5, 10
	v_lshl_add_u64 v[2:3], v[2:3], 0, v[112:113]
	v_mad_i64_i32 v[4:5], s[10:11], v0, s16, v[4:5]
	s_add_i32 s7, s7, 0
	s_mov_b32 s10, m0
	s_mov_b32 m0, s7
	s_nop 0
	global_load_lds_dwordx4 v[2:3], off
	s_mov_b32 m0, s10
	s_add_i32 s10, s7, 0x2000
	v_lshl_add_u64 v[6:7], v[2:3], 0, s[48:49]
	s_mov_b32 s11, m0
	s_mov_b32 m0, s10
	s_nop 0
	global_load_lds_dwordx4 v[6:7], off
	s_mov_b32 m0, s11
	v_lshl_add_u64 v[4:5], v[4:5], 0, v[112:113]
	s_add_i32 s9, s7, 0x4000
	s_mov_b32 s10, m0
	s_mov_b32 m0, s9
	s_nop 0
	global_load_lds_dwordx4 v[4:5], off
	s_mov_b32 m0, s10
	s_and_b32 s6, s5, 3
	s_add_i32 s10, s9, 0x2000
	s_mov_b64 s[30:31], 0x88000
	v_lshl_add_u64 v[6:7], v[4:5], 0, s[30:31]
	s_mov_b32 s11, m0
	s_mov_b32 m0, s10
	s_nop 0
	global_load_lds_dwordx4 v[6:7], off
	s_mov_b32 m0, s11
	s_lshl_b32 s10, s6, 5
	v_and_b32_e32 v8, 31, v68
	s_or_b32 s10, s10, s18
	v_or_b32_e32 v206, s10, v8
	v_ashrrev_i32_e32 v207, 31, v206
	v_readlane_b32 s10, v254, 56
	v_lshlrev_b64 v[6:7], 11, v[206:207]
	v_readlane_b32 s11, v254, 57
	v_bfe_u32 v235, v68, 5, 1
	v_lshlrev_b32_e32 v112, 4, v235
	v_lshl_add_u64 v[6:7], s[10:11], 0, v[6:7]
	s_lshl_b32 s10, s5, 4
	s_andn2_b32 s10, s10, 63
	v_lshl_add_u64 v[6:7], v[6:7], 0, s[72:73]
	s_ashr_i32 s11, s10, 31
	v_lshl_add_u64 v[6:7], s[10:11], 1, v[6:7]
	v_lshl_add_u64 v[6:7], v[6:7], 0, v[112:113]
	global_load_dwordx4 v[126:129], v[6:7], off
	global_load_dwordx4 v[122:125], v[6:7], off offset:32
	global_load_dwordx4 v[118:121], v[6:7], off offset:64
	global_load_dwordx4 v[114:117], v[6:7], off offset:96
	v_lshlrev_b32_e32 v1, 1, v68
	v_bfe_u32 v6, v68, 1, 5
	s_cmp_gt_u32 s5, 3
	v_mad_i64_i32 v[50:51], s[16:17], v0, s16, 0
	v_and_b32_e32 v0, 19, v68
	v_and_b32_e32 v1, 8, v1
	v_and_b32_e32 v7, 4, v6
	s_cselect_b64 s[18:19], -1, 0
	s_cmp_lt_u32 s5, 4
	v_or3_b32 v0, v1, v0, v7
	s_cselect_b64 s[16:17], -1, 0
	v_lshrrev_b32_e32 v1, 1, v0
	s_and_b64 s[36:37], s[16:17], exec
	v_bitop3_b32 v1, v1, v235, 7 bitop3:0x6c
	s_cselect_b32 s31, 0, 0x2000
	s_waitcnt vmcnt(0) lgkmcnt(0)
	s_barrier
	v_lshlrev_b32_e32 v244, 4, v1
	v_lshl_or_b32 v248, v0, 7, s31
	v_lshl_add_u64 v[0:1], v[2:3], 0, s[34:35]
	s_add_i32 s31, s7, 0x8000
	s_mov_b32 s36, m0
	s_mov_b32 m0, s31
	s_nop 0
	global_load_lds_dwordx4 v[0:1], off
	s_mov_b32 m0, s36
	s_mov_b64 s[36:37], 0x20080
	s_add_i32 s31, s7, 0xa000
	v_lshl_add_u64 v[0:1], v[2:3], 0, s[36:37]
	s_mov_b32 s36, m0
	s_mov_b32 m0, s31
	s_nop 0
	global_load_lds_dwordx4 v[0:1], off
	s_mov_b32 m0, s36
	v_bitop3_b32 v16, v6, v235, 7 bitop3:0x6c
	v_lshl_add_u64 v[6:7], v[4:5], 0, s[48:49]
	s_add_i32 s31, s9, 0x8000
	s_mov_b32 s36, m0
	s_mov_b32 m0, s31
	s_nop 0
	global_load_lds_dwordx4 v[6:7], off
	s_mov_b32 m0, s36
	s_mov_b64 s[36:37], 0x88080
	v_lshl_add_u64 v[0:1], v[4:5], 0, s[36:37]
	s_add_i32 s31, s9, 0xa000
	s_mov_b32 s36, m0
	s_mov_b32 m0, s31
	s_nop 0
	global_load_lds_dwordx4 v[0:1], off
	s_mov_b32 m0, s36
	s_mov_b64 s[36:37], 0x40000
	v_lshl_add_u64 v[0:1], v[2:3], 0, s[36:37]
	s_add_i32 s31, s7, 0x10000
	s_mov_b32 s36, m0
	s_mov_b32 m0, s31
	s_nop 0
	global_load_lds_dwordx4 v[0:1], off
	s_mov_b32 m0, s36
	s_mov_b64 s[36:37], 0x40080
	v_lshl_add_u64 v[0:1], v[2:3], 0, s[36:37]
	s_add_i32 s31, s7, 0x12000
	s_mov_b32 s36, m0
	s_mov_b32 m0, s31
	s_nop 0
	global_load_lds_dwordx4 v[0:1], off
	s_mov_b32 m0, s36
	s_mov_b64 s[36:37], 0x100
	v_lshl_add_u64 v[6:7], v[4:5], 0, s[36:37]
	s_add_i32 s31, s9, 0x10000
	s_mov_b32 s36, m0
	s_mov_b32 m0, s31
	s_nop 0
	global_load_lds_dwordx4 v[6:7], off
	s_mov_b32 m0, s36
	s_mov_b64 s[36:37], 0x88100
	v_lshl_add_u64 v[0:1], v[4:5], 0, s[36:37]
	s_add_i32 s31, s9, 0x12000
	s_mov_b32 s36, m0
	s_mov_b32 m0, s31
	s_nop 0
	global_load_lds_dwordx4 v[0:1], off
	s_mov_b32 m0, s36
	v_add_u32_e32 v0, 0, v248
	v_xor_b32_e32 v245, 32, v244
	v_xor_b32_e32 v246, 64, v244
	v_xor_b32_e32 v247, 0x60, v244
	v_add_u32_e32 v249, v0, v244
	v_lshlrev_b32_e32 v243, 7, v8
	v_add_u32_e32 v250, v0, v245
	v_add_u32_e32 v251, v0, v246
	v_add_u32_e32 v252, v0, v247
	ds_read_b128 v[0:3], v249
	ds_read_b128 v[4:7], v249 offset:4096
	ds_read_b128 v[8:11], v250
	ds_read_b128 v[12:15], v250 offset:4096
	ds_read_b128 v[52:55], v251
	ds_read_b128 v[56:59], v251 offset:4096
	ds_read_b128 v[60:63], v252
	ds_read_b128 v[64:67], v252 offset:4096
	v_lshlrev_b32_e32 v224, 4, v16
	s_mov_b32 s30, 0
	v_and_b32_e32 v236, 63, v68
	s_mov_b32 s10, 2
	s_mov_b32 s11, 1
	s_mov_b32 s100, 3
	v_xor_b32_e32 v242, 32, v224
	v_xor_b32_e32 v241, 64, v224
	v_xor_b32_e32 v239, 0x60, v224
	s_waitcnt lgkmcnt(0)
	v_mfma_f32_32x32x16_bf16 v[16:31], v[0:3], v[126:129], 0
	s_mov_b32 s72, s73
	s_mov_b32 s74, s73
	s_mov_b32 s75, s73
	s_mov_b32 s76, s73
	s_mov_b32 s77, s73
	s_mov_b32 s78, s73
	s_mov_b32 s79, s73
	v_mfma_f32_32x32x16_bf16 v[32:47], v[4:7], v[126:129], 0
	s_mov_b32 s80, s73
	s_mov_b32 s81, s73
	s_mov_b32 s82, s73
	s_mov_b32 s83, s73
	s_mov_b32 s84, s73
	s_mov_b32 s85, s73
	s_mov_b32 s86, s73
	v_mfma_f32_32x32x16_bf16 v[16:31], v[8:11], v[122:125], v[16:31]
	s_mov_b32 s87, s73
	v_mfma_f32_32x32x16_bf16 v[32:47], v[12:15], v[122:125], v[32:47]
	v_mov_b64_e32 v[0:1], s[72:73]
	v_mov_b64_e32 v[2:3], s[74:75]
	v_mov_b64_e32 v[4:5], s[76:77]
	v_mov_b64_e32 v[6:7], s[78:79]
	v_mov_b64_e32 v[8:9], s[80:81]
	v_mov_b64_e32 v[10:11], s[82:83]
	v_mov_b64_e32 v[12:13], s[84:85]
	v_mfma_f32_32x32x16_bf16 v[16:31], v[52:55], v[118:121], v[16:31]
	v_mov_b64_e32 v[14:15], s[86:87]
	v_readlane_b32 s86, v255, 35
	s_movk_i32 s75, 0x2000
	v_readlane_b32 s87, v255, 36
	v_mfma_f32_32x32x16_bf16 v[32:47], v[56:59], v[118:121], v[32:47]
	v_mfma_f32_32x32x16_bf16 v[16:31], v[60:63], v[114:117], v[16:31]
	v_mfma_f32_32x32x16_bf16 v[32:47], v[64:67], v[114:117], v[32:47]
	s_nop 11
	v_max_f32_e32 v52, v33, v33
	v_max_f32_e32 v53, v17, v17
	v_max_f32_e32 v52, v53, v52
	v_max_f32_e32 v53, v34, v34
	v_max_f32_e32 v54, v18, v18
	v_max_f32_e32 v53, v54, v53
	v_max_f32_e32 v54, v35, v35
	v_max_f32_e32 v55, v19, v19
	v_max3_f32 v52, v16, v32, v52
	v_max_f32_e32 v54, v55, v54
	v_max3_f32 v52, v52, v53, v54
	v_max_f32_e32 v53, v36, v36
	v_max_f32_e32 v54, v20, v20
	v_max_f32_e32 v53, v54, v53
	v_max_f32_e32 v54, v37, v37
	v_max_f32_e32 v55, v21, v21
	v_max_f32_e32 v54, v55, v54
	v_max3_f32 v52, v52, v53, v54
	v_max_f32_e32 v53, v38, v38
	v_max_f32_e32 v54, v22, v22
	v_max_f32_e32 v53, v54, v53
	v_max_f32_e32 v54, v39, v39
	v_max_f32_e32 v55, v23, v23
	v_max_f32_e32 v54, v55, v54
	v_max3_f32 v52, v52, v53, v54
	v_max_f32_e32 v53, v40, v40
	v_max_f32_e32 v54, v24, v24
	v_max_f32_e32 v53, v54, v53
	v_max_f32_e32 v54, v41, v41
	v_max_f32_e32 v55, v25, v25
	v_max_f32_e32 v54, v55, v54
	v_max3_f32 v52, v52, v53, v54
	v_max_f32_e32 v53, v42, v42
	v_max_f32_e32 v54, v26, v26
	v_max_f32_e32 v53, v54, v53
	v_max_f32_e32 v54, v43, v43
	v_max_f32_e32 v55, v27, v27
	v_max_f32_e32 v54, v55, v54
	v_max3_f32 v52, v52, v53, v54
	v_max_f32_e32 v53, v44, v44
	v_max_f32_e32 v54, v28, v28
	v_max_f32_e32 v53, v54, v53
	v_max_f32_e32 v54, v45, v45
	v_max_f32_e32 v55, v29, v29
	v_max_f32_e32 v54, v55, v54
	v_max3_f32 v52, v52, v53, v54
	v_max_f32_e32 v53, v46, v46
	v_max_f32_e32 v54, v30, v30
	v_max_f32_e32 v53, v54, v53
	v_max_f32_e32 v54, v47, v47
	v_max_f32_e32 v55, v31, v31
	v_max_f32_e32 v54, v55, v54
	v_max3_f32 v52, v52, v53, v54
	v_mov_b32_e32 v53, v52
	s_nop 1
	v_permlane32_swap_b32_e32 v52, v53
	v_max_f32_e32 v53, v53, v53
	v_max_f32_e32 v52, v52, v52
	v_max_f32_e32 v52, v52, v53
	s_mov_b32 s31, 0x41800000
	v_cmp_gt_f32_e64 vcc, |v52|, s31
	v_add_u32_e32 v240, 0, v243
	s_or_b32 s26, s27, s26
	v_cndmask_b32_e32 v209, 0, v52, vcc
	v_sub_f32_e32 v16, v16, v209
	v_sub_f32_e32 v17, v17, v209
	v_exp_f32_e32 v16, v16
	v_exp_f32_e32 v17, v17
	v_sub_f32_e32 v18, v18, v209
	v_exp_f32_e32 v18, v18
	v_sub_f32_e32 v19, v19, v209
	v_exp_f32_e32 v19, v19
	v_sub_f32_e32 v20, v20, v209
	v_exp_f32_e32 v20, v20
	v_sub_f32_e32 v21, v21, v209
	v_cvt_pk_bf16_f32 v178, v16, v17
	v_add_f32_e32 v16, 0, v16
	v_exp_f32_e32 v21, v21
	v_sub_f32_e32 v22, v22, v209
	v_add_f32_e32 v16, v17, v16
	v_exp_f32_e32 v22, v22
	v_sub_f32_e32 v23, v23, v209
	v_add_f32_e32 v16, v18, v16
	v_sub_f32_e32 v24, v24, v209
	v_exp_f32_e32 v23, v23
	v_add_f32_e32 v16, v19, v16
	v_exp_f32_e32 v24, v24
	v_sub_f32_e32 v25, v25, v209
	v_add_f32_e32 v16, v20, v16
	v_exp_f32_e32 v25, v25
	v_sub_f32_e32 v26, v26, v209
	v_add_f32_e32 v16, v21, v16
	v_exp_f32_e32 v26, v26
	v_sub_f32_e32 v27, v27, v209
	v_add_f32_e32 v16, v22, v16
	v_exp_f32_e32 v27, v27
	v_sub_f32_e32 v28, v28, v209
	v_add_f32_e32 v16, v23, v16
	v_exp_f32_e32 v28, v28
	v_sub_f32_e32 v29, v29, v209
	v_add_f32_e32 v16, v24, v16
	v_exp_f32_e32 v29, v29
	v_sub_f32_e32 v30, v30, v209
	v_add_f32_e32 v16, v25, v16
	v_exp_f32_e32 v30, v30
	v_sub_f32_e32 v31, v31, v209
	v_add_f32_e32 v16, v26, v16
	v_sub_f32_e32 v32, v32, v209
	v_exp_f32_e32 v31, v31
	v_add_f32_e32 v16, v27, v16
	v_exp_f32_e32 v32, v32
	v_sub_f32_e32 v33, v33, v209
	v_add_f32_e32 v16, v28, v16
	v_exp_f32_e32 v33, v33
	v_sub_f32_e32 v34, v34, v209
	v_add_f32_e32 v16, v29, v16
	v_exp_f32_e32 v34, v34
	v_sub_f32_e32 v35, v35, v209
	v_add_f32_e32 v16, v30, v16
	v_exp_f32_e32 v35, v35
	v_sub_f32_e32 v36, v36, v209
	v_add_f32_e32 v16, v31, v16
	v_exp_f32_e32 v36, v36
	v_sub_f32_e32 v37, v37, v209
	v_add_f32_e32 v16, v32, v16
	v_exp_f32_e32 v37, v37
	v_sub_f32_e32 v38, v38, v209
	v_add_f32_e32 v16, v33, v16
	v_exp_f32_e32 v38, v38
	v_sub_f32_e32 v39, v39, v209
	v_add_f32_e32 v16, v34, v16
	v_sub_f32_e32 v40, v40, v209
	v_exp_f32_e32 v39, v39
	v_add_f32_e32 v16, v35, v16
	v_exp_f32_e32 v40, v40
	v_sub_f32_e32 v41, v41, v209
	v_add_f32_e32 v16, v36, v16
	v_exp_f32_e32 v41, v41
	v_sub_f32_e32 v42, v42, v209
	v_add_f32_e32 v16, v37, v16
	v_exp_f32_e32 v42, v42
	v_sub_f32_e32 v43, v43, v209
	v_add_f32_e32 v16, v38, v16
	v_exp_f32_e32 v43, v43
	v_sub_f32_e32 v44, v44, v209
	v_add_f32_e32 v16, v39, v16
	v_exp_f32_e32 v44, v44
	v_sub_f32_e32 v45, v45, v209
	v_add_f32_e32 v16, v40, v16
	v_exp_f32_e32 v45, v45
	v_sub_f32_e32 v46, v46, v209
	v_add_f32_e32 v16, v41, v16
	v_exp_f32_e32 v46, v46
	v_sub_f32_e32 v47, v47, v209
	v_add_f32_e32 v16, v42, v16
	v_exp_f32_e32 v47, v47
	v_add_f32_e32 v16, v43, v16
	v_add_f32_e32 v16, v44, v16
	v_add_f32_e32 v16, v45, v16
	v_add_f32_e32 v16, v46, v16
	v_add_u32_e32 v237, v240, v224
	v_cvt_pk_bf16_f32 v179, v18, v19
	v_add_f32_e32 v238, v47, v16
	v_mad_i64_i32 v[16:17], s[26:27], s26, v226, v[50:51]
	v_bitop3_b32 v18, v69, 7, v68 bitop3:0x48
	ds_read_b128 v[190:193], v237 offset:16384
	ds_read_b128 v[186:189], v237 offset:20480
	ds_read_b128 v[182:185], v237 offset:24576
	ds_read_b128 v[142:145], v237 offset:28672
	v_lshlrev_b32_e32 v18, 4, v18
	v_readlane_b32 s26, v255, 10
	v_or_b32_e32 v16, v16, v18
	v_readlane_b32 s27, v255, 11
	s_waitcnt vmcnt(0) lgkmcnt(0)
	s_barrier
	v_cvt_pk_bf16_f32 v130, v40, v41
	v_cvt_pk_bf16_f32 v131, v42, v43
	v_lshl_add_u64 v[210:211], s[26:27], 0, v[16:17]
	v_mad_i64_i32 v[16:17], s[26:27], s25, v225, v[48:49]
	v_or3_b32 v16, v16, s24, v18
	v_readlane_b32 s24, v255, 14
	v_readlane_b32 s25, v255, 15
	v_cvt_pk_bf16_f32 v132, v44, v45
	v_cvt_pk_bf16_f32 v133, v46, v47
	v_cvt_pk_bf16_f32 v134, v32, v33
	v_cvt_pk_bf16_f32 v135, v34, v35
	v_cvt_pk_bf16_f32 v136, v36, v37
	v_cvt_pk_bf16_f32 v137, v38, v39
	v_cvt_pk_bf16_f32 v138, v24, v25
	v_cvt_pk_bf16_f32 v139, v26, v27
	v_cvt_pk_bf16_f32 v140, v28, v29
	v_cvt_pk_bf16_f32 v141, v30, v31
	v_cvt_pk_bf16_f32 v180, v20, v21
	v_cvt_pk_bf16_f32 v181, v22, v23
	v_lshl_add_u64 v[212:213], s[24:25], 0, v[16:17]
	v_mov_b64_e32 v[62:63], v[14:15]
	v_mov_b64_e32 v[46:47], v[14:15]
	v_mov_b64_e32 v[30:31], v[14:15]
	s_mov_b64 s[26:27], 0
	v_mov_b64_e32 v[60:61], v[12:13]
	v_mov_b64_e32 v[58:59], v[10:11]
	v_mov_b64_e32 v[56:57], v[8:9]
	v_mov_b64_e32 v[54:55], v[6:7]
	v_mov_b64_e32 v[52:53], v[4:5]
	v_mov_b64_e32 v[50:51], v[2:3]
	v_mov_b64_e32 v[48:49], v[0:1]
	v_mov_b64_e32 v[44:45], v[12:13]
	v_mov_b64_e32 v[42:43], v[10:11]
	v_mov_b64_e32 v[40:41], v[8:9]
	v_mov_b64_e32 v[38:39], v[6:7]
	v_mov_b64_e32 v[36:37], v[4:5]
	v_mov_b64_e32 v[34:35], v[2:3]
	v_mov_b64_e32 v[32:33], v[0:1]
	v_mov_b64_e32 v[28:29], v[12:13]
	v_mov_b64_e32 v[26:27], v[10:11]
	v_mov_b64_e32 v[24:25], v[8:9]
	v_mov_b64_e32 v[22:23], v[6:7]
	v_mov_b64_e32 v[20:21], v[4:5]
	v_mov_b64_e32 v[18:19], v[2:3]
	v_mov_b64_e32 v[16:17], v[0:1]

.LBB1_522:
	s_mov_b32 s24, s30
	v_cvt_pk_bf16_f32 v178, v80, v81
	v_cvt_pk_bf16_f32 v179, v82, v83
	v_cvt_pk_bf16_f32 v180, v84, v85
	v_cvt_pk_bf16_f32 v181, v86, v87
	v_cvt_pk_bf16_f32 v138, v88, v89
	v_cvt_pk_bf16_f32 v139, v90, v91
	v_cvt_pk_bf16_f32 v140, v92, v93
	v_cvt_pk_bf16_f32 v141, v94, v95
	v_cvt_pk_bf16_f32 v134, v96, v97
	v_cvt_pk_bf16_f32 v135, v98, v99
	v_cvt_pk_bf16_f32 v136, v100, v101
	v_cvt_pk_bf16_f32 v137, v102, v103
	v_cvt_pk_bf16_f32 v130, v104, v105
	v_cvt_pk_bf16_f32 v131, v106, v107
	v_cvt_pk_bf16_f32 v132, v108, v109
	v_cvt_pk_bf16_f32 v133, v110, v111
	v_cmp_neq_f32_e64 s[36:37], 0, v209
	v_xor_b32_e32 v64, 0x80000000, v209
.Lat_qk:
	s_mov_b64 vcc, s[36:37]
	s_cbranch_vccz .LBB1_532
	s_lshl_b32 s25, s100, 15
	s_add_i32 s30, s25, s7
	v_lshl_add_u64 v[72:73], v[212:213], 0, s[34:35]
	s_mov_b32 s31, m0
	s_mov_b32 m0, s30
	s_nop 0
	global_load_lds_dwordx4 v[72:73], off
	s_mov_b32 m0, s31
	s_addk_i32 s30, 0x2000
	v_lshl_add_u64 v[66:67], v[72:73], 0, s[48:49]
	s_mov_b32 s31, m0
	s_mov_b32 m0, s30
	s_nop 0
	global_load_lds_dwordx4 v[66:67], off
	s_mov_b32 m0, s31
	s_add_u32 s30, s26, 0x80
	s_addc_u32 s31, s27, 0
	v_lshl_add_u64 v[68:69], v[210:211], 0, s[30:31]
	s_add_i32 s25, s25, s9
	s_mov_b32 s30, m0
	s_mov_b32 m0, s25
	s_nop 0
	global_load_lds_dwordx4 v[68:69], off
	s_mov_b32 m0, s30
	s_addk_i32 s25, 0x2000
	s_mov_b64 s[30:31], 0x88000
	v_lshl_add_u64 v[70:71], v[68:69], 0, s[30:31]
	s_mov_b32 s30, m0
	s_mov_b32 m0, s25
	s_nop 0
	global_load_lds_dwordx4 v[70:71], off
	s_mov_b32 m0, s30
	s_lshl_b32 s25, s11, 15
	v_mov_b32_e32 v65, v64
	v_pk_mov_b32 v[66:67], v[64:65], v[64:65]
	v_pk_mov_b32 v[68:69], v[64:65], v[64:65]
	v_pk_mov_b32 v[70:71], v[64:65], v[64:65]
	v_pk_mov_b32 v[72:73], v[64:65], v[64:65]
	v_pk_mov_b32 v[74:75], v[64:65], v[64:65]
	v_pk_mov_b32 v[76:77], v[64:65], v[64:65]
	v_pk_mov_b32 v[78:79], v[64:65], v[64:65]
	s_waitcnt lgkmcnt(7)
	v_mfma_f32_32x32x16_bf16 v[80:95], v[166:169], v[126:129], v[64:79]
	s_waitcnt lgkmcnt(6)
	v_mfma_f32_32x32x16_bf16 v[96:111], v[174:177], v[126:129], v[64:79]
	s_waitcnt lgkmcnt(5)
	v_mfma_f32_32x32x16_bf16 v[80:95], v[170:173], v[122:125], v[80:95]
	s_waitcnt lgkmcnt(4)
	v_mfma_f32_32x32x16_bf16 v[96:111], v[162:165], v[122:125], v[96:111]
	s_waitcnt lgkmcnt(3)
	v_mfma_f32_32x32x16_bf16 v[80:95], v[158:161], v[118:121], v[80:95]
	s_waitcnt lgkmcnt(2)
	v_mfma_f32_32x32x16_bf16 v[96:111], v[154:157], v[118:121], v[96:111]
	s_waitcnt lgkmcnt(1)
	v_mfma_f32_32x32x16_bf16 v[80:95], v[150:153], v[114:117], v[80:95]
	s_waitcnt lgkmcnt(0)
	v_mfma_f32_32x32x16_bf16 v[96:111], v[146:149], v[114:117], v[96:111]
	s_cbranch_execnz .LBB1_525
.LBB1_524:
	s_waitcnt lgkmcnt(7)
	v_mfma_f32_32x32x16_bf16 v[80:95], v[166:169], v[126:129], 0
	s_waitcnt lgkmcnt(6)
	v_mfma_f32_32x32x16_bf16 v[96:111], v[174:177], v[126:129], 0
	s_lshl_b32 s25, s100, 15
	s_add_i32 s30, s25, s7
	v_lshl_add_u64 v[72:73], v[212:213], 0, s[34:35]
	s_mov_b32 s31, m0
	s_mov_b32 m0, s30
	s_nop 0
	global_load_lds_dwordx4 v[72:73], off
	s_mov_b32 m0, s31
	s_waitcnt lgkmcnt(5)
	v_mfma_f32_32x32x16_bf16 v[80:95], v[170:173], v[122:125], v[80:95]
	s_waitcnt lgkmcnt(4)
	v_mfma_f32_32x32x16_bf16 v[96:111], v[162:165], v[122:125], v[96:111]
	s_addk_i32 s30, 0x2000
	v_lshl_add_u64 v[66:67], v[72:73], 0, s[48:49]
	s_mov_b32 s31, m0
	s_mov_b32 m0, s30
	s_nop 0
	global_load_lds_dwordx4 v[66:67], off
	s_mov_b32 m0, s31
	s_waitcnt lgkmcnt(3)
	v_mfma_f32_32x32x16_bf16 v[80:95], v[158:161], v[118:121], v[80:95]
	s_waitcnt lgkmcnt(2)
	v_mfma_f32_32x32x16_bf16 v[96:111], v[154:157], v[118:121], v[96:111]
	s_add_u32 s30, s26, 0x80
	s_addc_u32 s31, s27, 0
	v_lshl_add_u64 v[68:69], v[210:211], 0, s[30:31]
	s_add_i32 s25, s25, s9
	s_mov_b32 s30, m0
	s_mov_b32 m0, s25
	s_nop 0
	global_load_lds_dwordx4 v[68:69], off
	s_mov_b32 m0, s30
	s_waitcnt lgkmcnt(1)
	v_mfma_f32_32x32x16_bf16 v[80:95], v[150:153], v[114:117], v[80:95]
	s_waitcnt lgkmcnt(0)
	v_mfma_f32_32x32x16_bf16 v[96:111], v[146:149], v[114:117], v[96:111]
	s_addk_i32 s25, 0x2000
	s_mov_b64 s[30:31], 0x88000
	v_lshl_add_u64 v[70:71], v[68:69], 0, s[30:31]
	s_mov_b32 s30, m0
	s_mov_b32 m0, s25
	s_nop 0
	global_load_lds_dwordx4 v[70:71], off
	s_mov_b32 m0, s30
	s_lshl_b32 s25, s11, 15

.LBB1_530:
	v_add3_u32 v64, s25, v243, v224
	ds_read_b128 v[190:193], v64 offset:16384
	ds_read_b128 v[186:189], v64 offset:20480
	ds_read_b128 v[182:185], v64 offset:24576
	ds_read_b128 v[142:145], v64 offset:28672
	v_add_f32_e32 v238, v66, v238
	s_lshl_b32 s25, s10, 15
	v_add_u32_e32 v64, s25, v248
	v_add_u32_e32 v65, v64, v244
	v_add_u32_e32 v66, v64, v245
	v_add_u32_e32 v67, v64, v246
	v_add_u32_e32 v64, v64, v247
	ds_read_b128 v[166:169], v65
	ds_read_b128 v[174:177], v65 offset:4096
	ds_read_b128 v[170:173], v66
	ds_read_b128 v[162:165], v66 offset:4096
	ds_read_b128 v[158:161], v67
	ds_read_b128 v[154:157], v67 offset:4096
	ds_read_b128 v[150:153], v64
	ds_read_b128 v[146:149], v64 offset:4096
	s_waitcnt vmcnt(0)
	s_barrier
	s_add_u32 s26, s26, 0x80
	s_addc_u32 s27, s27, 0
	s_cmpk_eq_i32 s26, 0x2100
	v_lshl_add_u64 v[212:213], v[212:213], 0, s[34:35]
	s_cbranch_scc1 .Lat_exit
	s_mov_b32 s30, s11
	s_mov_b32 s11, s10
	s_mov_b32 s10, s100
	s_mov_b32 s100, s24
	s_branch .LBB1_522

.Lat_exit:
	s_waitcnt lgkmcnt(0)
	v_cvt_pk_bf16_f32 v178, v80, v81
	v_cvt_pk_bf16_f32 v179, v82, v83
	v_cvt_pk_bf16_f32 v180, v84, v85
	v_cvt_pk_bf16_f32 v181, v86, v87
	v_cvt_pk_bf16_f32 v138, v88, v89
	v_cvt_pk_bf16_f32 v139, v90, v91
	v_cvt_pk_bf16_f32 v140, v92, v93
	v_cvt_pk_bf16_f32 v141, v94, v95
	v_cvt_pk_bf16_f32 v134, v96, v97
	v_cvt_pk_bf16_f32 v135, v98, v99
	v_cvt_pk_bf16_f32 v136, v100, v101
	v_cvt_pk_bf16_f32 v137, v102, v103
	v_cvt_pk_bf16_f32 v130, v104, v105
	v_cvt_pk_bf16_f32 v131, v106, v107
	v_cvt_pk_bf16_f32 v132, v108, v109
	v_cvt_pk_bf16_f32 v133, v110, v111
	v_add_u32_e32 v249, 0x10000, v249
	v_add_u32_e32 v250, 0x10000, v250
	v_add_u32_e32 v251, 0x10000, v251
	v_add_u32_e32 v252, 0x10000, v252
	v_add_u32_e32 v240, 0x10000, v240
	v_add_u32_e32 v237, 0x10000, v237

	.amdhsa_kernel _Z4mega4Args
		.amdhsa_group_segment_fixed_size 0
		.amdhsa_private_segment_fixed_size 0
		.amdhsa_kernarg_size 448
		.amdhsa_user_sgpr_count 2
		.amdhsa_user_sgpr_dispatch_ptr 0
		.amdhsa_user_sgpr_queue_ptr 0
		.amdhsa_user_sgpr_kernarg_segment_ptr 1
		.amdhsa_user_sgpr_dispatch_id 0
		.amdhsa_user_sgpr_kernarg_preload_length 0
		.amdhsa_user_sgpr_kernarg_preload_offset 0
		.amdhsa_user_sgpr_private_segment_size 0
		.amdhsa_uses_dynamic_stack 0
		.amdhsa_enable_private_segment 0
		.amdhsa_system_sgpr_workgroup_id_x 1
		.amdhsa_system_sgpr_workgroup_id_y 0
		.amdhsa_system_sgpr_workgroup_id_z 0
		.amdhsa_system_sgpr_workgroup_info 0
		.amdhsa_system_vgpr_workitem_id 0
		.amdhsa_next_free_vgpr 256
		.amdhsa_next_free_sgpr 102
		.amdhsa_accum_offset 256
		.amdhsa_reserve_vcc 1
		.amdhsa_float_round_mode_32 0
		.amdhsa_float_round_mode_16_64 0
		.amdhsa_float_denorm_mode_32 3
		.amdhsa_float_denorm_mode_16_64 3
		.amdhsa_dx10_clamp 1
		.amdhsa_ieee_mode 1
		.amdhsa_fp16_overflow 0
		.amdhsa_tg_split 0
		.amdhsa_exception_fp_ieee_invalid_op 0
		.amdhsa_exception_fp_denorm_src 0
		.amdhsa_exception_fp_ieee_div_zero 0
		.amdhsa_exception_fp_ieee_overflow 0
		.amdhsa_exception_fp_ieee_underflow 0
		.amdhsa_exception_fp_ieee_inexact 0
		.amdhsa_exception_int_div_zero 0
	.end_amdhsa_kernel

amdhsa.kernels:
  - .agpr_count:     0
    .args:
      - .offset:         0
        .size:           176
        .value_kind:     by_value
      - .offset:         176
        .size:           4
        .value_kind:     by_value
    .group_segment_fixed_size: 35328
    .kernarg_segment_align: 8
    .kernarg_segment_size: 180
    .language:       OpenCL C
    .language_version:
      - 2
      - 0
    .max_flat_workgroup_size: 64
    .name:           _Z7k_sattn6Paramsi
    .private_segment_fixed_size: 0
    .sgpr_count:     27
    .sgpr_spill_count: 0
    .symbol:         _Z7k_sattn6Paramsi.kd
    .uniform_work_group_size: 1
    .uses_dynamic_stack: false
    .vgpr_count:     167
    .vgpr_spill_count: 0
    .wavefront_size: 64
  - .agpr_count:     0
    .args:
      - .offset:         0
        .size:           192
        .value_kind:     by_value
      - .offset:         192
        .size:           4
        .value_kind:     hidden_block_count_x
      - .offset:         196
        .size:           4
        .value_kind:     hidden_block_count_y
      - .offset:         200
        .size:           4
        .value_kind:     hidden_block_count_z
      - .offset:         204
        .size:           2
        .value_kind:     hidden_group_size_x
      - .offset:         206
        .size:           2
        .value_kind:     hidden_group_size_y
      - .offset:         208
        .size:           2
        .value_kind:     hidden_group_size_z
      - .offset:         210
        .size:           2
        .value_kind:     hidden_remainder_x
      - .offset:         212
        .size:           2
        .value_kind:     hidden_remainder_y
      - .offset:         214
        .size:           2
        .value_kind:     hidden_remainder_z
      - .offset:         232
        .size:           8
        .value_kind:     hidden_global_offset_x
      - .offset:         240
        .size:           8
        .value_kind:     hidden_global_offset_y
      - .offset:         248
        .size:           8
        .value_kind:     hidden_global_offset_z
      - .offset:         256
        .size:           2
        .value_kind:     hidden_grid_dims
      - .offset:         312
        .size:           4
        .value_kind:     hidden_dynamic_lds_size
    .group_segment_fixed_size: 0
    .kernarg_segment_align: 8
    .kernarg_segment_size: 448
    .language:       OpenCL C
    .language_version:
      - 2
      - 0
    .max_flat_workgroup_size: 512
    .name:           _Z4mega4Args
    .private_segment_fixed_size: 0
    .sgpr_count:     108
    .sgpr_spill_count: 189
    .symbol:         _Z4mega4Args.kd
    .uniform_work_group_size: 1
    .uses_dynamic_stack: false
    .vgpr_count:     256
    .vgpr_spill_count: 0
    .wavefront_size: 64
